# radix-select pass loops: all four independent loads issued before the first wait (hipcc had serialized the first one)
# baseline (speedup 1.0000x reference)
; DI void phase_select(KArgs args, LAS unsigned char* L, const Ctx& c, int inst) {
;     ...
;         for (int i = tid * 4; i < n; i += 512 * 16) {
;             u32x4 x4[4];
; #pragma unroll
;             for (int k = 0; k < 4; ++k) x4[k] = *(const u32x4*)(v + i + k * 2048);
; #pragma unroll
;             for (int k = 0; k < 4; ++k)
; #pragma unroll
;                 for (int j = 0; j < 4; ++j) { const unsigned x = x4[k][j]; if ((x & mhi) == prefix) __hip_atomic_fetch_add(&hist[(x >> shift) & bmask], 1u, __ATOMIC_RELAXED, __HIP_MEMORY_SCOPE_WORKGROUP); } }
.LBB0_532:
	v_add_co_u32_e32 v4, vcc, 0x2000, v26
	global_load_dwordx4 v[16:19], v[26:27], off
	s_nop 0
	v_addc_co_u32_e32 v5, vcc, 0, v27, vcc
	v_add_co_u32_e32 v6, vcc, 0x4000, v26
	s_nop 1
	v_addc_co_u32_e32 v7, vcc, 0, v27, vcc
	global_load_dwordx4 v[12:15], v[4:5], off
	global_load_dwordx4 v[8:11], v[6:7], off
	v_add_co_u32_e32 v4, vcc, 0x6000, v26
	s_nop 1
	v_addc_co_u32_e32 v5, vcc, 0, v27, vcc
	global_load_dwordx4 v[4:7], v[4:5], off
	s_waitcnt vmcnt(3)
	v_and_b32_e32 v31, s41, v16
	v_cmp_eq_u32_e32 vcc, v31, v30
	s_and_saveexec_b64 s[38:39], vcc
	v_lshrrev_b32_e32 v16, s44, v16
	v_and_b32_e32 v16, s40, v16
	v_lshl_add_u32 v16, v16, 2, 0
	ds_add_u32 v16, v210
	s_or_b64 exec, exec, s[38:39]
	v_and_b32_e32 v16, s41, v17
	v_cmp_eq_u32_e32 vcc, v16, v30
	s_and_saveexec_b64 s[38:39], vcc
	v_lshrrev_b32_e32 v16, s44, v17
	v_and_b32_e32 v16, s40, v16
	v_lshl_add_u32 v16, v16, 2, 0
	ds_add_u32 v16, v210
	s_or_b64 exec, exec, s[38:39]
	v_and_b32_e32 v16, s41, v18
	v_cmp_eq_u32_e32 vcc, v16, v30
	s_and_saveexec_b64 s[38:39], vcc
	v_lshrrev_b32_e32 v16, s44, v18
	v_and_b32_e32 v16, s40, v16
	v_lshl_add_u32 v16, v16, 2, 0
	ds_add_u32 v16, v210
	s_or_b64 exec, exec, s[38:39]
	v_and_b32_e32 v16, s41, v19
	v_cmp_eq_u32_e32 vcc, v16, v30
	s_and_saveexec_b64 s[38:39], vcc
	v_lshrrev_b32_e32 v16, s44, v19
	v_and_b32_e32 v16, s40, v16
	v_lshl_add_u32 v16, v16, 2, 0
	ds_add_u32 v16, v210
	s_or_b64 exec, exec, s[38:39]
	s_waitcnt vmcnt(2)
	v_and_b32_e32 v16, s41, v12
	v_cmp_eq_u32_e32 vcc, v16, v30
	s_and_saveexec_b64 s[38:39], vcc
	v_lshrrev_b32_e32 v12, s44, v12
	v_and_b32_e32 v12, s40, v12
	v_lshl_add_u32 v12, v12, 2, 0
	ds_add_u32 v12, v210
	s_or_b64 exec, exec, s[38:39]
	v_and_b32_e32 v12, s41, v13
	v_cmp_eq_u32_e32 vcc, v12, v30
	s_and_saveexec_b64 s[38:39], vcc
	v_lshrrev_b32_e32 v12, s44, v13
	v_and_b32_e32 v12, s40, v12
	v_lshl_add_u32 v12, v12, 2, 0
	ds_add_u32 v12, v210
	s_or_b64 exec, exec, s[38:39]
	v_and_b32_e32 v12, s41, v14
	v_cmp_eq_u32_e32 vcc, v12, v30
	s_and_saveexec_b64 s[38:39], vcc
	v_lshrrev_b32_e32 v12, s44, v14
	v_and_b32_e32 v12, s40, v12
	v_lshl_add_u32 v12, v12, 2, 0
	ds_add_u32 v12, v210
	s_or_b64 exec, exec, s[38:39]
	v_and_b32_e32 v12, s41, v15
	v_cmp_eq_u32_e32 vcc, v12, v30
	s_and_saveexec_b64 s[38:39], vcc
	v_lshrrev_b32_e32 v12, s44, v15
	v_and_b32_e32 v12, s40, v12
	v_lshl_add_u32 v12, v12, 2, 0
	ds_add_u32 v12, v210
	s_or_b64 exec, exec, s[38:39]
	s_waitcnt vmcnt(1)
	v_and_b32_e32 v12, s41, v8
	v_cmp_eq_u32_e32 vcc, v12, v30
	s_and_saveexec_b64 s[38:39], vcc
	v_lshrrev_b32_e32 v8, s44, v8
	v_and_b32_e32 v8, s40, v8
	v_lshl_add_u32 v8, v8, 2, 0
	ds_add_u32 v8, v210
	s_or_b64 exec, exec, s[38:39]
	v_and_b32_e32 v8, s41, v9
	v_cmp_eq_u32_e32 vcc, v8, v30
	s_and_saveexec_b64 s[38:39], vcc
	v_lshrrev_b32_e32 v8, s44, v9
	v_and_b32_e32 v8, s40, v8
	v_lshl_add_u32 v8, v8, 2, 0
	ds_add_u32 v8, v210
	s_or_b64 exec, exec, s[38:39]
	v_and_b32_e32 v8, s41, v10
	v_cmp_eq_u32_e32 vcc, v8, v30
	s_and_saveexec_b64 s[38:39], vcc
	v_lshrrev_b32_e32 v8, s44, v10
	v_and_b32_e32 v8, s40, v8
	v_lshl_add_u32 v8, v8, 2, 0
	ds_add_u32 v8, v210
	s_or_b64 exec, exec, s[38:39]
	v_and_b32_e32 v8, s41, v11
	v_cmp_eq_u32_e32 vcc, v8, v30
	s_and_saveexec_b64 s[38:39], vcc
	v_lshrrev_b32_e32 v8, s44, v11
	v_and_b32_e32 v8, s40, v8
	v_lshl_add_u32 v8, v8, 2, 0
	ds_add_u32 v8, v210
	s_or_b64 exec, exec, s[38:39]
	s_waitcnt vmcnt(0)
	v_and_b32_e32 v8, s41, v4
	v_cmp_eq_u32_e32 vcc, v8, v30
	s_and_saveexec_b64 s[38:39], vcc
	v_lshrrev_b32_e32 v4, s44, v4
	v_and_b32_e32 v4, s40, v4
	v_lshl_add_u32 v4, v4, 2, 0
	ds_add_u32 v4, v210
	s_or_b64 exec, exec, s[38:39]
	v_and_b32_e32 v4, s41, v5
	v_cmp_eq_u32_e32 vcc, v4, v30
	s_and_saveexec_b64 s[38:39], vcc
	v_lshrrev_b32_e32 v4, s44, v5
	v_and_b32_e32 v4, s40, v4
	v_lshl_add_u32 v4, v4, 2, 0
	ds_add_u32 v4, v210
	s_or_b64 exec, exec, s[38:39]
	v_and_b32_e32 v4, s41, v6
	v_cmp_eq_u32_e32 vcc, v4, v30
	s_and_saveexec_b64 s[38:39], vcc
	v_lshrrev_b32_e32 v4, s44, v6
	v_and_b32_e32 v4, s40, v4
	v_lshl_add_u32 v4, v4, 2, 0
	ds_add_u32 v4, v210
	s_or_b64 exec, exec, s[38:39]
	v_and_b32_e32 v4, s41, v7
	v_cmp_eq_u32_e32 vcc, v4, v30
	s_and_saveexec_b64 s[38:39], vcc
	s_cbranch_execz .LBB0_531
	v_lshrrev_b32_e32 v4, s44, v7
	v_and_b32_e32 v4, s40, v4
	v_lshl_add_u32 v4, v4, 2, 0
	ds_add_u32 v4, v210
	s_branch .LBB0_531

; DI void phase_select(KArgs args, LAS unsigned char* L, const Ctx& c, int inst) {
;     ...
;         for (int i = tid * 4; i < n; i += 512 * 16) {
;             u32x4 x4[4];
; #pragma unroll
;             for (int k = 0; k < 4; ++k) x4[k] = *(const u32x4*)(v + i + k * 2048);
; #pragma unroll
;             for (int k = 0; k < 4; ++k)
; #pragma unroll
;                 for (int j = 0; j < 4; ++j) { const unsigned x = x4[k][j]; if ((x & mhi) == prefix) __hip_atomic_fetch_add(&hist[(x >> shift) & bmask], 1u, __ATOMIC_RELAXED, __HIP_MEMORY_SCOPE_WORKGROUP); } }
.LBB0_1282:
	v_add_co_u32_e32 v4, vcc, 0x2000, v26
	global_load_dwordx4 v[16:19], v[26:27], off
	s_nop 0
	v_addc_co_u32_e32 v5, vcc, 0, v27, vcc
	v_add_co_u32_e32 v6, vcc, 0x4000, v26
	s_nop 1
	v_addc_co_u32_e32 v7, vcc, 0, v27, vcc
	global_load_dwordx4 v[12:15], v[4:5], off
	global_load_dwordx4 v[8:11], v[6:7], off
	v_add_co_u32_e32 v4, vcc, 0x6000, v26
	s_nop 1
	v_addc_co_u32_e32 v5, vcc, 0, v27, vcc
	global_load_dwordx4 v[4:7], v[4:5], off
	s_waitcnt vmcnt(3)
	v_and_b32_e32 v30, s50, v16
	v_cmp_eq_u32_e32 vcc, v30, v29
	s_and_saveexec_b64 s[42:43], vcc
	v_lshrrev_b32_e32 v16, s48, v16
	v_and_b32_e32 v16, s49, v16
	v_lshl_add_u32 v16, v16, 2, 0
	ds_add_u32 v16, v210
	s_or_b64 exec, exec, s[42:43]
	v_and_b32_e32 v16, s50, v17
	v_cmp_eq_u32_e32 vcc, v16, v29
	s_and_saveexec_b64 s[42:43], vcc
	v_lshrrev_b32_e32 v16, s48, v17
	v_and_b32_e32 v16, s49, v16
	v_lshl_add_u32 v16, v16, 2, 0
	ds_add_u32 v16, v210
	s_or_b64 exec, exec, s[42:43]
	v_and_b32_e32 v16, s50, v18
	v_cmp_eq_u32_e32 vcc, v16, v29
	s_and_saveexec_b64 s[42:43], vcc
	v_lshrrev_b32_e32 v16, s48, v18
	v_and_b32_e32 v16, s49, v16
	v_lshl_add_u32 v16, v16, 2, 0
	ds_add_u32 v16, v210
	s_or_b64 exec, exec, s[42:43]
	v_and_b32_e32 v16, s50, v19
	v_cmp_eq_u32_e32 vcc, v16, v29
	s_and_saveexec_b64 s[42:43], vcc
	v_lshrrev_b32_e32 v16, s48, v19
	v_and_b32_e32 v16, s49, v16
	v_lshl_add_u32 v16, v16, 2, 0
	ds_add_u32 v16, v210
	s_or_b64 exec, exec, s[42:43]
	s_waitcnt vmcnt(2)
	v_and_b32_e32 v16, s50, v12
	v_cmp_eq_u32_e32 vcc, v16, v29
	s_and_saveexec_b64 s[42:43], vcc
	v_lshrrev_b32_e32 v12, s48, v12
	v_and_b32_e32 v12, s49, v12
	v_lshl_add_u32 v12, v12, 2, 0
	ds_add_u32 v12, v210
	s_or_b64 exec, exec, s[42:43]
	v_and_b32_e32 v12, s50, v13
	v_cmp_eq_u32_e32 vcc, v12, v29
	s_and_saveexec_b64 s[42:43], vcc
	v_lshrrev_b32_e32 v12, s48, v13
	v_and_b32_e32 v12, s49, v12
	v_lshl_add_u32 v12, v12, 2, 0
	ds_add_u32 v12, v210
	s_or_b64 exec, exec, s[42:43]
	v_and_b32_e32 v12, s50, v14
	v_cmp_eq_u32_e32 vcc, v12, v29
	s_and_saveexec_b64 s[42:43], vcc
	v_lshrrev_b32_e32 v12, s48, v14
	v_and_b32_e32 v12, s49, v12
	v_lshl_add_u32 v12, v12, 2, 0
	ds_add_u32 v12, v210
	s_or_b64 exec, exec, s[42:43]
	v_and_b32_e32 v12, s50, v15
	v_cmp_eq_u32_e32 vcc, v12, v29
	s_and_saveexec_b64 s[42:43], vcc
	v_lshrrev_b32_e32 v12, s48, v15
	v_and_b32_e32 v12, s49, v12
	v_lshl_add_u32 v12, v12, 2, 0
	ds_add_u32 v12, v210
	s_or_b64 exec, exec, s[42:43]
	s_waitcnt vmcnt(1)
	v_and_b32_e32 v12, s50, v8
	v_cmp_eq_u32_e32 vcc, v12, v29
	s_and_saveexec_b64 s[42:43], vcc
	v_lshrrev_b32_e32 v8, s48, v8
	v_and_b32_e32 v8, s49, v8
	v_lshl_add_u32 v8, v8, 2, 0
	ds_add_u32 v8, v210
	s_or_b64 exec, exec, s[42:43]
	v_and_b32_e32 v8, s50, v9
	v_cmp_eq_u32_e32 vcc, v8, v29
	s_and_saveexec_b64 s[42:43], vcc
	v_lshrrev_b32_e32 v8, s48, v9
	v_and_b32_e32 v8, s49, v8
	v_lshl_add_u32 v8, v8, 2, 0
	ds_add_u32 v8, v210
	s_or_b64 exec, exec, s[42:43]
	v_and_b32_e32 v8, s50, v10
	v_cmp_eq_u32_e32 vcc, v8, v29
	s_and_saveexec_b64 s[42:43], vcc
	v_lshrrev_b32_e32 v8, s48, v10
	v_and_b32_e32 v8, s49, v8
	v_lshl_add_u32 v8, v8, 2, 0
	ds_add_u32 v8, v210
	s_or_b64 exec, exec, s[42:43]
	v_and_b32_e32 v8, s50, v11
	v_cmp_eq_u32_e32 vcc, v8, v29
	s_and_saveexec_b64 s[42:43], vcc
	v_lshrrev_b32_e32 v8, s48, v11
	v_and_b32_e32 v8, s49, v8
	v_lshl_add_u32 v8, v8, 2, 0
	ds_add_u32 v8, v210
	s_or_b64 exec, exec, s[42:43]
	s_waitcnt vmcnt(0)
	v_and_b32_e32 v8, s50, v4
	v_cmp_eq_u32_e32 vcc, v8, v29
	s_and_saveexec_b64 s[42:43], vcc
	v_lshrrev_b32_e32 v4, s48, v4
	v_and_b32_e32 v4, s49, v4
	v_lshl_add_u32 v4, v4, 2, 0
	ds_add_u32 v4, v210
	s_or_b64 exec, exec, s[42:43]
	v_and_b32_e32 v4, s50, v5
	v_cmp_eq_u32_e32 vcc, v4, v29
	s_and_saveexec_b64 s[42:43], vcc
	v_lshrrev_b32_e32 v4, s48, v5
	v_and_b32_e32 v4, s49, v4
	v_lshl_add_u32 v4, v4, 2, 0
	ds_add_u32 v4, v210
	s_or_b64 exec, exec, s[42:43]
	v_and_b32_e32 v4, s50, v6
	v_cmp_eq_u32_e32 vcc, v4, v29
	s_and_saveexec_b64 s[42:43], vcc
	v_lshrrev_b32_e32 v4, s48, v6
	v_and_b32_e32 v4, s49, v4
	v_lshl_add_u32 v4, v4, 2, 0
	ds_add_u32 v4, v210
	s_or_b64 exec, exec, s[42:43]
	v_and_b32_e32 v4, s50, v7
	v_cmp_eq_u32_e32 vcc, v4, v29
	s_and_saveexec_b64 s[42:43], vcc
	s_cbranch_execz .LBB0_1281
	v_lshrrev_b32_e32 v4, s48, v7
	v_and_b32_e32 v4, s49, v4
	v_lshl_add_u32 v4, v4, 2, 0
	ds_add_u32 v4, v210
	s_branch .LBB0_1281
